# lever 8 MFMA-VALU interleave: attention softmax exps/cvts of P chunks 1-3 moved into the shadows of the PV MFMAs (two P fragment sets, running row-sum)
# speedup vs baseline: 1.0013x; 1.0010x over previous
; #define LAS __attribute__((address_space(3)))
; __device__ __forceinline__ void attn_unit(LAS unsigned char* lds, const bf16_t* Q, const bf16_t* KN, const bf16_t* KPE, const bf16_t* VT, bf16_t* Y, float* ssq_b, int b, int h, int qg) {
;     ...
;             const float mn = upd ? fmaxf(mrun, mx) : mrun; const float alpha = upd ? fexp2(mrun - mn) : 1.0f; mrun = mn;
;             s0 = s0 - mn; s1 = s1 - mn;
; #pragma unroll
;             for (int i = 0; i < 16; ++i) { s0[i] = fexp2(s0[i]); s1[i] = fexp2(s1[i]); }
;             const f32x16 t16 = s0 + s1;
;             typedef float f32x8_ __attribute__((ext_vector_type(8)));
;             const f32x8_ t8 = __builtin_shufflevector(t16, t16, 0, 1, 2, 3, 4, 5, 6, 7) + __builtin_shufflevector(t16, t16, 8, 9, 10, 11, 12, 13, 14, 15);
;             const f32x4 t4 = __builtin_shufflevector(t8, t8, 0, 1, 2, 3) + __builtin_shufflevector(t8, t8, 4, 5, 6, 7);
;             const float ps = (t4[0] + t4[1]) + (t4[2] + t4[3]);
;             lsum = lsum * alpha + ps;
;             if (upd) {
; #pragma unroll
;                 for (int d = 0; d < 4; ++d)
; #pragma unroll
;                     for (int i = 0; i < 16; ++i) o[d][i] *= alpha;
;             }
; #pragma unroll
;             for (int kb2 = 0; kb2 < 2; ++kb2)
; #pragma unroll
;                 for (int a = 0; a < 2; ++a) {
;                     u32x4 pw;
;                     if (kb2 == 0) { pw.x = cvt_pk(s0[8 * a + 0], s0[8 * a + 1]); pw.y = cvt_pk(s0[8 * a + 2], s0[8 * a + 3]); pw.z = cvt_pk(s0[8 * a + 4], s0[8 * a + 5]); pw.w = cvt_pk(s0[8 * a + 6], s0[8 * a + 7]); }
;                     else { pw.x = cvt_pk(s1[8 * a + 0], s1[8 * a + 1]); pw.y = cvt_pk(s1[8 * a + 2], s1[8 * a + 3]); pw.z = cvt_pk(s1[8 * a + 4], s1[8 * a + 5]); pw.w = cvt_pk(s1[8 * a + 6], s1[8 * a + 7]); }
;                     const bf16x8 pf = __builtin_bit_cast(bf16x8, pw);
;                     const unsigned vro = vbase0 ^ (unsigned)((4 * kb2 + 2 * a) << 4);
;                     __builtin_amdgcn_s_setprio(1);
; #pragma unroll
;                     for (int db = 0; db < 4; ++db) {
;                         const bf16x8 vf = *(const LAS bf16x8*)(vb + (vro + (unsigned)(db * 4096)));
;                         o[db] = __builtin_amdgcn_mfma_f32_32x32x16_bf16(vf, pf, o[db], 0, 0, 0);
;                     }
;                     __builtin_amdgcn_s_setprio(0);
;                 }
.LBB0_668:
	v_sub_f32_e32 v95, v95, v159
	v_sub_f32_e32 v94, v94, v159
	v_sub_f32_e32 v93, v93, v159
	v_sub_f32_e32 v92, v92, v159
	v_sub_f32_e32 v91, v91, v159
	v_sub_f32_e32 v90, v90, v159
	v_sub_f32_e32 v89, v89, v159
	v_sub_f32_e32 v88, v88, v159
	v_sub_f32_e32 v87, v87, v159
	v_sub_f32_e32 v86, v86, v159
	v_sub_f32_e32 v85, v85, v159
	v_sub_f32_e32 v84, v84, v159
	v_sub_f32_e32 v83, v83, v159
	v_sub_f32_e32 v82, v82, v159
	v_sub_f32_e32 v81, v81, v159
	v_sub_f32_e32 v80, v80, v159
	v_sub_f32_e32 v163, v79, v159
	v_sub_f32_e32 v167, v78, v159
	v_sub_f32_e32 v177, v77, v159
	v_sub_f32_e32 v217, v76, v159
	v_sub_f32_e32 v218, v75, v159
	v_sub_f32_e32 v219, v74, v159
	v_sub_f32_e32 v220, v73, v159
	v_sub_f32_e32 v221, v72, v159
	v_sub_f32_e32 v79, v71, v159
	v_sub_f32_e32 v71, v70, v159
	v_sub_f32_e32 v70, v69, v159
	v_sub_f32_e32 v69, v68, v159
	v_sub_f32_e32 v68, v67, v159
	v_sub_f32_e32 v67, v66, v159
	v_sub_f32_e32 v66, v65, v159
	v_sub_f32_e32 v65, v64, v159
	v_exp_f32_e32 v64, v80
	v_exp_f32_e32 v72, v65
	v_exp_f32_e32 v65, v81
	v_exp_f32_e32 v73, v66
	v_exp_f32_e32 v66, v82
	v_exp_f32_e32 v74, v67
	v_exp_f32_e32 v67, v83
	v_exp_f32_e32 v75, v68
	v_exp_f32_e32 v68, v84
	v_exp_f32_e32 v76, v69
	v_exp_f32_e32 v69, v85
	v_exp_f32_e32 v77, v70
	v_exp_f32_e32 v70, v86
	v_exp_f32_e32 v78, v71
	v_exp_f32_e32 v71, v87
	v_exp_f32_e32 v79, v79
	v_pk_add_f32 v[238:239], v[64:65], v[66:67]
	v_pk_add_f32 v[238:239], v[238:239], v[68:69]
	v_pk_add_f32 v[238:239], v[238:239], v[70:71]
	ds_read_b128 v[222:225], v252 offset:32768
	ds_read_b128 v[226:229], v252 offset:36864
	ds_read_b128 v[230:233], v253 offset:24576
	v_cvt_pk_bf16_f32 v64, v64, v65
	v_cvt_pk_bf16_f32 v65, v66, v67
	v_cvt_pk_bf16_f32 v66, v68, v69
	v_cvt_pk_bf16_f32 v67, v70, v71
	s_setprio 1
	s_waitcnt lgkmcnt(4)
	v_mfma_f32_32x32x16_bf16 v[48:63], v[244:247], v[64:67], v[48:63]
	ds_read_b128 v[244:247], v253 offset:28672
	v_exp_f32_e32 v80, v88
	v_exp_f32_e32 v81, v89
	s_waitcnt lgkmcnt(4)
	v_mfma_f32_32x32x16_bf16 v[32:47], v[248:251], v[64:67], v[32:47]
	ds_read_b128 v[248:251], v253 offset:32768
	v_cvt_pk_bf16_f32 v234, v80, v81
	v_exp_f32_e32 v84, v90
	v_exp_f32_e32 v85, v91
	v_pk_add_f32 v[238:239], v[238:239], v[72:73]
	s_waitcnt lgkmcnt(4)
	v_mfma_f32_32x32x16_bf16 v[16:31], v[222:225], v[64:67], v[16:31]
	ds_read_b128 v[222:225], v253 offset:36864
	v_cvt_pk_bf16_f32 v235, v84, v85
	v_exp_f32_e32 v88, v92
	v_exp_f32_e32 v89, v93
	v_pk_add_f32 v[238:239], v[238:239], v[74:75]
	s_waitcnt lgkmcnt(4)
	v_mfma_f32_32x32x16_bf16 v[0:15], v[226:229], v[64:67], v[0:15]
	ds_read_b128 v[226:229], v254 offset:24576
	v_cvt_pk_bf16_f32 v236, v88, v89
	v_exp_f32_e32 v92, v94
	v_exp_f32_e32 v93, v95
	v_pk_add_f32 v[238:239], v[238:239], v[76:77]
	v_cvt_pk_bf16_f32 v237, v92, v93
	v_pk_add_f32 v[238:239], v[238:239], v[78:79]
	s_waitcnt lgkmcnt(4)
	v_mfma_f32_32x32x16_bf16 v[48:63], v[230:233], v[234:237], v[48:63]
	ds_read_b128 v[230:233], v254 offset:28672
	v_cvt_pk_bf16_f32 v64, v72, v73
	v_exp_f32_e32 v82, v221
	v_exp_f32_e32 v83, v220
	v_pk_add_f32 v[238:239], v[238:239], v[80:81]
	s_waitcnt lgkmcnt(4)
	v_mfma_f32_32x32x16_bf16 v[32:47], v[244:247], v[234:237], v[32:47]
	ds_read_b128 v[244:247], v254 offset:32768
	v_cvt_pk_bf16_f32 v65, v74, v75
	v_exp_f32_e32 v86, v219
	v_exp_f32_e32 v87, v218
	v_pk_add_f32 v[238:239], v[238:239], v[84:85]
	s_waitcnt lgkmcnt(4)
	v_mfma_f32_32x32x16_bf16 v[16:31], v[248:251], v[234:237], v[16:31]
	ds_read_b128 v[248:251], v254 offset:36864
	v_cvt_pk_bf16_f32 v66, v76, v77
	v_exp_f32_e32 v90, v217
	v_exp_f32_e32 v91, v177
	v_pk_add_f32 v[238:239], v[238:239], v[88:89]
	s_waitcnt lgkmcnt(4)
	v_mfma_f32_32x32x16_bf16 v[0:15], v[222:225], v[234:237], v[0:15]
	ds_read_b128 v[222:225], v255 offset:24576
	v_cvt_pk_bf16_f32 v67, v78, v79
	v_exp_f32_e32 v94, v167
	v_exp_f32_e32 v95, v163
	v_pk_add_f32 v[238:239], v[238:239], v[92:93]
	s_waitcnt lgkmcnt(4)
	v_mfma_f32_32x32x16_bf16 v[48:63], v[226:229], v[64:67], v[48:63]
	ds_read_b128 v[226:229], v255 offset:28672
	v_cvt_pk_bf16_f32 v234, v82, v83
	v_pk_add_f32 v[238:239], v[238:239], v[82:83]
	s_waitcnt lgkmcnt(4)
	v_mfma_f32_32x32x16_bf16 v[32:47], v[230:233], v[64:67], v[32:47]
	ds_read_b128 v[230:233], v255 offset:32768
	v_cvt_pk_bf16_f32 v235, v86, v87
	v_pk_add_f32 v[238:239], v[238:239], v[86:87]
	s_waitcnt lgkmcnt(4)
	v_mfma_f32_32x32x16_bf16 v[16:31], v[244:247], v[64:67], v[16:31]
	ds_read_b128 v[244:247], v255 offset:36864
	v_cvt_pk_bf16_f32 v236, v90, v91
	v_pk_add_f32 v[238:239], v[238:239], v[90:91]
	s_waitcnt lgkmcnt(4)
	v_mfma_f32_32x32x16_bf16 v[0:15], v[248:251], v[64:67], v[0:15]
	v_cvt_pk_bf16_f32 v237, v94, v95
	v_pk_add_f32 v[238:239], v[238:239], v[94:95]
	s_nop 0
	s_waitcnt lgkmcnt(3)
	v_mfma_f32_32x32x16_bf16 v[48:63], v[222:225], v[234:237], v[48:63]
	v_add_f32_e32 v167, v238, v239
	v_cndmask_b32_e64 v163, v196, 1.0, s[52:53]
	s_waitcnt lgkmcnt(2)
	v_mfma_f32_32x32x16_bf16 v[32:47], v[226:229], v[234:237], v[32:47]
	s_nop 0
	v_fmac_f32_e32 v167, v157, v163
	s_waitcnt lgkmcnt(1)
	v_mfma_f32_32x32x16_bf16 v[16:31], v[230:233], v[234:237], v[16:31]
	s_waitcnt lgkmcnt(0)
	v_mfma_f32_32x32x16_bf16 v[0:15], v[244:247], v[234:237], v[0:15]
	s_setprio 0
	v_mov_b32_e32 v157, v167
	s_branch .LBB0_670

; #define LAS __attribute__((address_space(3)))
; __device__ __forceinline__ void attn_unit(LAS unsigned char* lds, const bf16_t* Q, const bf16_t* KN, const bf16_t* KPE, const bf16_t* VT, bf16_t* Y, float* ssq_b, int b, int h, int qg) {
;     ...
;             const float mn = upd ? fmaxf(mrun, mx) : mrun; const float alpha = upd ? fexp2(mrun - mn) : 1.0f; mrun = mn;
;             s0 = s0 - mn; s1 = s1 - mn;
; #pragma unroll
;             for (int i = 0; i < 16; ++i) { s0[i] = fexp2(s0[i]); s1[i] = fexp2(s1[i]); }
;             const f32x16 t16 = s0 + s1;
;             typedef float f32x8_ __attribute__((ext_vector_type(8)));
;             const f32x8_ t8 = __builtin_shufflevector(t16, t16, 0, 1, 2, 3, 4, 5, 6, 7) + __builtin_shufflevector(t16, t16, 8, 9, 10, 11, 12, 13, 14, 15);
;             const f32x4 t4 = __builtin_shufflevector(t8, t8, 0, 1, 2, 3) + __builtin_shufflevector(t8, t8, 4, 5, 6, 7);
;             const float ps = (t4[0] + t4[1]) + (t4[2] + t4[3]);
;             lsum = lsum * alpha + ps;
;             if (upd) {
; #pragma unroll
;                 for (int d = 0; d < 4; ++d)
; #pragma unroll
;                     for (int i = 0; i < 16; ++i) o[d][i] *= alpha;
;             }
; #pragma unroll
;             for (int kb2 = 0; kb2 < 2; ++kb2)
; #pragma unroll
;                 for (int a = 0; a < 2; ++a) {
;                     u32x4 pw;
;                     if (kb2 == 0) { pw.x = cvt_pk(s0[8 * a + 0], s0[8 * a + 1]); pw.y = cvt_pk(s0[8 * a + 2], s0[8 * a + 3]); pw.z = cvt_pk(s0[8 * a + 4], s0[8 * a + 5]); pw.w = cvt_pk(s0[8 * a + 6], s0[8 * a + 7]); }
;                     else { pw.x = cvt_pk(s1[8 * a + 0], s1[8 * a + 1]); pw.y = cvt_pk(s1[8 * a + 2], s1[8 * a + 3]); pw.z = cvt_pk(s1[8 * a + 4], s1[8 * a + 5]); pw.w = cvt_pk(s1[8 * a + 6], s1[8 * a + 7]); }
;                     const bf16x8 pf = __builtin_bit_cast(bf16x8, pw);
;                     const unsigned vro = vbase0 ^ (unsigned)((4 * kb2 + 2 * a) << 4);
;                     __builtin_amdgcn_s_setprio(1);
; #pragma unroll
;                     for (int db = 0; db < 4; ++db) {
;                         const bf16x8 vf = *(const LAS bf16x8*)(vb + (vro + (unsigned)(db * 4096)));
;                         o[db] = __builtin_amdgcn_mfma_f32_32x32x16_bf16(vf, pf, o[db], 0, 0, 0);
;                     }
;                     __builtin_amdgcn_s_setprio(0);
;                 }
.LBB0_696:
	v_sub_f32_e32 v95, v95, v159
	v_sub_f32_e32 v94, v94, v159
	v_sub_f32_e32 v93, v93, v159
	v_sub_f32_e32 v92, v92, v159
	v_sub_f32_e32 v91, v91, v159
	v_sub_f32_e32 v90, v90, v159
	v_sub_f32_e32 v89, v89, v159
	v_sub_f32_e32 v88, v88, v159
	v_sub_f32_e32 v87, v87, v159
	v_sub_f32_e32 v86, v86, v159
	v_sub_f32_e32 v85, v85, v159
	v_sub_f32_e32 v84, v84, v159
	v_sub_f32_e32 v83, v83, v159
	v_sub_f32_e32 v82, v82, v159
	v_sub_f32_e32 v81, v81, v159
	v_sub_f32_e32 v80, v80, v159
	v_sub_f32_e32 v163, v79, v159
	v_sub_f32_e32 v167, v78, v159
	v_sub_f32_e32 v177, v77, v159
	v_sub_f32_e32 v207, v76, v159
	v_sub_f32_e32 v208, v75, v159
	v_sub_f32_e32 v209, v74, v159
	v_sub_f32_e32 v210, v73, v159
	v_sub_f32_e32 v211, v72, v159
	v_sub_f32_e32 v79, v71, v159
	v_sub_f32_e32 v71, v70, v159
	v_sub_f32_e32 v70, v69, v159
	v_sub_f32_e32 v69, v68, v159
	v_sub_f32_e32 v68, v67, v159
	v_sub_f32_e32 v67, v66, v159
	v_sub_f32_e32 v66, v65, v159
	v_sub_f32_e32 v65, v64, v159
	v_exp_f32_e32 v64, v80
	v_exp_f32_e32 v72, v65
	v_exp_f32_e32 v65, v81
	v_exp_f32_e32 v73, v66
	v_exp_f32_e32 v66, v82
	v_exp_f32_e32 v74, v67
	v_exp_f32_e32 v67, v83
	v_exp_f32_e32 v75, v68
	v_exp_f32_e32 v68, v84
	v_exp_f32_e32 v76, v69
	v_exp_f32_e32 v69, v85
	v_exp_f32_e32 v77, v70
	v_exp_f32_e32 v70, v86
	v_exp_f32_e32 v78, v71
	v_exp_f32_e32 v71, v87
	v_exp_f32_e32 v79, v79
	v_pk_add_f32 v[238:239], v[64:65], v[66:67]
	v_pk_add_f32 v[238:239], v[238:239], v[68:69]
	v_pk_add_f32 v[238:239], v[238:239], v[70:71]
	ds_read_b128 v[214:217], v252 offset:32768
	ds_read_b128 v[218:221], v252 offset:36864
	ds_read_b128 v[222:225], v253 offset:24576
	v_cvt_pk_bf16_f32 v64, v64, v65
	v_cvt_pk_bf16_f32 v65, v66, v67
	v_cvt_pk_bf16_f32 v66, v68, v69
	v_cvt_pk_bf16_f32 v67, v70, v71
	s_setprio 1
	s_waitcnt lgkmcnt(4)
	v_mfma_f32_32x32x16_bf16 v[48:63], v[244:247], v[64:67], v[48:63]
	ds_read_b128 v[244:247], v253 offset:28672
	v_exp_f32_e32 v80, v88
	v_exp_f32_e32 v81, v89
	s_waitcnt lgkmcnt(4)
	v_mfma_f32_32x32x16_bf16 v[32:47], v[248:251], v[64:67], v[32:47]
	ds_read_b128 v[248:251], v253 offset:32768
	v_cvt_pk_bf16_f32 v234, v80, v81
	v_exp_f32_e32 v84, v90
	v_exp_f32_e32 v85, v91
	v_pk_add_f32 v[238:239], v[238:239], v[72:73]
	s_waitcnt lgkmcnt(4)
	v_mfma_f32_32x32x16_bf16 v[16:31], v[214:217], v[64:67], v[16:31]
	ds_read_b128 v[214:217], v253 offset:36864
	v_cvt_pk_bf16_f32 v235, v84, v85
	v_exp_f32_e32 v88, v92
	v_exp_f32_e32 v89, v93
	v_pk_add_f32 v[238:239], v[238:239], v[74:75]
	s_waitcnt lgkmcnt(4)
	v_mfma_f32_32x32x16_bf16 v[0:15], v[218:221], v[64:67], v[0:15]
	ds_read_b128 v[218:221], v254 offset:24576
	v_cvt_pk_bf16_f32 v236, v88, v89
	v_exp_f32_e32 v92, v94
	v_exp_f32_e32 v93, v95
	v_pk_add_f32 v[238:239], v[238:239], v[76:77]
	v_cvt_pk_bf16_f32 v237, v92, v93
	v_pk_add_f32 v[238:239], v[238:239], v[78:79]
	s_waitcnt lgkmcnt(4)
	v_mfma_f32_32x32x16_bf16 v[48:63], v[222:225], v[234:237], v[48:63]
	ds_read_b128 v[222:225], v254 offset:28672
	v_cvt_pk_bf16_f32 v64, v72, v73
	v_exp_f32_e32 v82, v211
	v_exp_f32_e32 v83, v210
	v_pk_add_f32 v[238:239], v[238:239], v[80:81]
	s_waitcnt lgkmcnt(4)
	v_mfma_f32_32x32x16_bf16 v[32:47], v[244:247], v[234:237], v[32:47]
	ds_read_b128 v[244:247], v254 offset:32768
	v_cvt_pk_bf16_f32 v65, v74, v75
	v_exp_f32_e32 v86, v209
	v_exp_f32_e32 v87, v208
	v_pk_add_f32 v[238:239], v[238:239], v[84:85]
	s_waitcnt lgkmcnt(4)
	v_mfma_f32_32x32x16_bf16 v[16:31], v[248:251], v[234:237], v[16:31]
	ds_read_b128 v[248:251], v254 offset:36864
	v_cvt_pk_bf16_f32 v66, v76, v77
	v_exp_f32_e32 v90, v207
	v_exp_f32_e32 v91, v177
	v_pk_add_f32 v[238:239], v[238:239], v[88:89]
	s_waitcnt lgkmcnt(4)
	v_mfma_f32_32x32x16_bf16 v[0:15], v[214:217], v[234:237], v[0:15]
	ds_read_b128 v[214:217], v255 offset:24576
	v_cvt_pk_bf16_f32 v67, v78, v79
	v_exp_f32_e32 v94, v167
	v_exp_f32_e32 v95, v163
	v_pk_add_f32 v[238:239], v[238:239], v[92:93]
	s_waitcnt lgkmcnt(4)
	v_mfma_f32_32x32x16_bf16 v[48:63], v[218:221], v[64:67], v[48:63]
	ds_read_b128 v[218:221], v255 offset:28672
	v_cvt_pk_bf16_f32 v234, v82, v83
	v_pk_add_f32 v[238:239], v[238:239], v[82:83]
	s_waitcnt lgkmcnt(4)
	v_mfma_f32_32x32x16_bf16 v[32:47], v[222:225], v[64:67], v[32:47]
	ds_read_b128 v[222:225], v255 offset:32768
	v_cvt_pk_bf16_f32 v235, v86, v87
	v_pk_add_f32 v[238:239], v[238:239], v[86:87]
	s_waitcnt lgkmcnt(4)
	v_mfma_f32_32x32x16_bf16 v[16:31], v[244:247], v[64:67], v[16:31]
	ds_read_b128 v[244:247], v255 offset:36864
	v_cvt_pk_bf16_f32 v236, v90, v91
	v_pk_add_f32 v[238:239], v[238:239], v[90:91]
	s_waitcnt lgkmcnt(4)
	v_mfma_f32_32x32x16_bf16 v[0:15], v[248:251], v[64:67], v[0:15]
	v_cvt_pk_bf16_f32 v237, v94, v95
	v_pk_add_f32 v[238:239], v[238:239], v[94:95]
	s_nop 0
	s_waitcnt lgkmcnt(3)
	v_mfma_f32_32x32x16_bf16 v[48:63], v[214:217], v[234:237], v[48:63]
	v_add_f32_e32 v167, v238, v239
	v_cndmask_b32_e64 v163, v196, 1.0, s[52:53]
	s_waitcnt lgkmcnt(2)
	v_mfma_f32_32x32x16_bf16 v[32:47], v[218:221], v[234:237], v[32:47]
	s_nop 0
	v_fmac_f32_e32 v167, v157, v163
	s_waitcnt lgkmcnt(1)
	v_mfma_f32_32x32x16_bf16 v[16:31], v[222:225], v[234:237], v[16:31]
	s_waitcnt lgkmcnt(0)
	v_mfma_f32_32x32x16_bf16 v[0:15], v[244:247], v[234:237], v[0:15]
	s_setprio 0
	v_mov_b32_e32 v157, v167
	s_branch .LBB0_698
